# v84 + phase_scan (HGRN inter-chunk scan) software-pipelined: 36 serialized load->fma->store round trips replaced by a depth-15 rolling prefetch with counted vmcnt waits (same f32 math, same order)
# speedup vs baseline: 1.0173x; 1.0144x over previous
.LBB0_383:
	v_ashrrev_i32_e32 v0, 11, v10
	v_mul_i32_i24_e32 v4, 36, v0
	v_ashrrev_i32_e32 v5, 31, v4
	v_and_b32_e32 v6, 0x7ff, v10
	v_lshlrev_b64 v[2:3], 13, v[4:5]
	v_lshl_add_u64 v[0:1], s[2:3], 0, v[2:3]
	v_lshlrev_b32_e32 v160, 2, v6
	v_lshl_add_u64 v[2:3], s[16:17], 0, v[2:3]
	v_lshlrev_b32_e32 v6, 3, v10
	v_lshl_add_u64 v[0:1], v[0:1], 0, v[160:161]
	v_lshl_add_u64 v[2:3], v[2:3], 0, v[160:161]
	v_and_b32_e32 v160, 0xf8, v6
	v_and_b32_e32 v6, 0x800, v10
	v_lshlrev_b64 v[4:5], 8, v[4:5]
	v_cmp_eq_u32_e64 s[40:41], 0, v6
	v_and_b32_e32 v6, 0x800, v10
	v_lshl_add_u64 v[4:5], s[18:19], 0, v[4:5]
	v_cmp_ne_u32_e64 s[42:43], 0, v6
	v_mov_b32_e32 v6, 0
	v_lshl_add_u64 v[4:5], v[4:5], 0, v[160:161]
	v_mov_b32_e32 v7, v6
	v_mov_b32_e32 v8, 0x6000
	v_mov_b32_e32 v9, 0x0
	v_cndmask_b32_e64 v160, v8, v9, s[40:41]
	v_lshl_add_u64 v[12:13], v[0:1], 0, v[160:161]
	v_lshrrev_b32_e32 v160, 5, v160
	v_lshl_add_u64 v[14:15], v[4:5], 0, v[160:161]
	s_nop 1
	global_load_dword v228, v[12:13], off
	global_load_dwordx2 v[196:197], v[14:15], off
	v_mov_b32_e32 v8, 0x4000
	v_mov_b32_e32 v9, 0x2000
	v_cndmask_b32_e64 v160, v8, v9, s[40:41]
	v_lshl_add_u64 v[12:13], v[0:1], 0, v[160:161]
	v_lshrrev_b32_e32 v160, 5, v160
	v_lshl_add_u64 v[14:15], v[4:5], 0, v[160:161]
	s_nop 1
	global_load_dword v229, v[12:13], off
	global_load_dwordx2 v[198:199], v[14:15], off
	v_mov_b32_e32 v8, 0x2000
	v_mov_b32_e32 v9, 0x4000
	v_cndmask_b32_e64 v160, v8, v9, s[40:41]
	v_lshl_add_u64 v[12:13], v[0:1], 0, v[160:161]
	v_lshrrev_b32_e32 v160, 5, v160
	v_lshl_add_u64 v[14:15], v[4:5], 0, v[160:161]
	s_nop 1
	global_load_dword v230, v[12:13], off
	global_load_dwordx2 v[200:201], v[14:15], off
	v_mov_b32_e32 v8, 0x0
	v_mov_b32_e32 v9, 0x6000
	v_cndmask_b32_e64 v160, v8, v9, s[40:41]
	v_lshl_add_u64 v[12:13], v[0:1], 0, v[160:161]
	v_lshrrev_b32_e32 v160, 5, v160
	v_lshl_add_u64 v[14:15], v[4:5], 0, v[160:161]
	s_nop 1
	global_load_dword v231, v[12:13], off
	global_load_dwordx2 v[202:203], v[14:15], off
	v_mov_b32_e32 v8, 0x46000
	v_mov_b32_e32 v9, 0x8000
	v_cndmask_b32_e64 v160, v8, v9, s[40:41]
	v_lshl_add_u64 v[12:13], v[0:1], 0, v[160:161]
	v_lshrrev_b32_e32 v160, 5, v160
	v_lshl_add_u64 v[14:15], v[4:5], 0, v[160:161]
	s_nop 1
	global_load_dword v232, v[12:13], off
	global_load_dwordx2 v[206:207], v[14:15], off
	v_mov_b32_e32 v8, 0x44000
	v_mov_b32_e32 v9, 0xa000
	v_cndmask_b32_e64 v160, v8, v9, s[40:41]
	v_lshl_add_u64 v[12:13], v[0:1], 0, v[160:161]
	v_lshrrev_b32_e32 v160, 5, v160
	v_lshl_add_u64 v[14:15], v[4:5], 0, v[160:161]
	s_nop 1
	global_load_dword v233, v[12:13], off
	global_load_dwordx2 v[208:209], v[14:15], off
	v_mov_b32_e32 v8, 0x42000
	v_mov_b32_e32 v9, 0xc000
	v_cndmask_b32_e64 v160, v8, v9, s[40:41]
	v_lshl_add_u64 v[12:13], v[0:1], 0, v[160:161]
	v_lshrrev_b32_e32 v160, 5, v160
	v_lshl_add_u64 v[14:15], v[4:5], 0, v[160:161]
	s_nop 1
	global_load_dword v234, v[12:13], off
	global_load_dwordx2 v[210:211], v[14:15], off
	v_mov_b32_e32 v8, 0x40000
	v_mov_b32_e32 v9, 0xe000
	v_cndmask_b32_e64 v160, v8, v9, s[40:41]
	v_lshl_add_u64 v[12:13], v[0:1], 0, v[160:161]
	v_lshrrev_b32_e32 v160, 5, v160
	v_lshl_add_u64 v[14:15], v[4:5], 0, v[160:161]
	s_nop 1
	global_load_dword v235, v[12:13], off
	global_load_dwordx2 v[212:213], v[14:15], off
	v_mov_b32_e32 v8, 0x3e000
	v_mov_b32_e32 v9, 0x10000
	v_cndmask_b32_e64 v160, v8, v9, s[40:41]
	v_lshl_add_u64 v[12:13], v[0:1], 0, v[160:161]
	v_lshrrev_b32_e32 v160, 5, v160
	v_lshl_add_u64 v[14:15], v[4:5], 0, v[160:161]
	s_nop 1
	global_load_dword v240, v[12:13], off
	global_load_dwordx2 v[214:215], v[14:15], off
	v_mov_b32_e32 v8, 0x3c000
	v_mov_b32_e32 v9, 0x12000
	v_cndmask_b32_e64 v160, v8, v9, s[40:41]
	v_lshl_add_u64 v[12:13], v[0:1], 0, v[160:161]
	v_lshrrev_b32_e32 v160, 5, v160
	v_lshl_add_u64 v[14:15], v[4:5], 0, v[160:161]
	s_nop 1
	global_load_dword v241, v[12:13], off
	global_load_dwordx2 v[216:217], v[14:15], off
	v_mov_b32_e32 v8, 0x3a000
	v_mov_b32_e32 v9, 0x14000
	v_cndmask_b32_e64 v160, v8, v9, s[40:41]
	v_lshl_add_u64 v[12:13], v[0:1], 0, v[160:161]
	v_lshrrev_b32_e32 v160, 5, v160
	v_lshl_add_u64 v[14:15], v[4:5], 0, v[160:161]
	s_nop 1
	global_load_dword v242, v[12:13], off
	global_load_dwordx2 v[218:219], v[14:15], off
	v_mov_b32_e32 v8, 0x38000
	v_mov_b32_e32 v9, 0x16000
	v_cndmask_b32_e64 v160, v8, v9, s[40:41]
	v_lshl_add_u64 v[12:13], v[0:1], 0, v[160:161]
	v_lshrrev_b32_e32 v160, 5, v160
	v_lshl_add_u64 v[14:15], v[4:5], 0, v[160:161]
	s_nop 1
	global_load_dword v243, v[12:13], off
	global_load_dwordx2 v[220:221], v[14:15], off
	v_mov_b32_e32 v8, 0x36000
	v_mov_b32_e32 v9, 0x18000
	v_cndmask_b32_e64 v160, v8, v9, s[40:41]
	v_lshl_add_u64 v[12:13], v[0:1], 0, v[160:161]
	v_lshrrev_b32_e32 v160, 5, v160
	v_lshl_add_u64 v[14:15], v[4:5], 0, v[160:161]
	s_nop 1
	global_load_dword v248, v[12:13], off
	global_load_dwordx2 v[222:223], v[14:15], off
	v_mov_b32_e32 v8, 0x34000
	v_mov_b32_e32 v9, 0x1a000
	v_cndmask_b32_e64 v160, v8, v9, s[40:41]
	v_lshl_add_u64 v[12:13], v[0:1], 0, v[160:161]
	v_lshrrev_b32_e32 v160, 5, v160
	v_lshl_add_u64 v[14:15], v[4:5], 0, v[160:161]
	s_nop 1
	global_load_dword v249, v[12:13], off
	global_load_dwordx2 v[224:225], v[14:15], off
	v_mov_b32_e32 v8, 0x32000
	v_mov_b32_e32 v9, 0x1c000
	v_cndmask_b32_e64 v160, v8, v9, s[40:41]
	v_lshl_add_u64 v[12:13], v[0:1], 0, v[160:161]
	v_lshrrev_b32_e32 v160, 5, v160
	v_lshl_add_u64 v[14:15], v[4:5], 0, v[160:161]
	s_nop 1
	global_load_dword v250, v[12:13], off
	global_load_dwordx2 v[226:227], v[14:15], off
	v_mov_b32_e32 v8, 0x6000
	v_mov_b32_e32 v9, 0x0
	v_cndmask_b32_e64 v160, v8, v9, s[40:41]
	v_lshl_add_u64 v[12:13], v[2:3], 0, v[160:161]
	v_cvt_pk_bf16_f32 v11, v6, v7
	s_nop 1
	global_store_dword v[12:13], v11, off
	s_waitcnt vmcnt(29)
	v_lshlrev_b32_e32 v14, 16, v228
	v_and_b32_e32 v15, 0xffff0000, v228
	s_nop 0
	v_pk_fma_f32 v[6:7], v[6:7], v[196:197], v[14:15]
	v_mov_b32_e32 v8, 0x30000
	v_mov_b32_e32 v9, 0x1e000
	v_cndmask_b32_e64 v160, v8, v9, s[40:41]
	v_lshl_add_u64 v[12:13], v[0:1], 0, v[160:161]
	v_lshrrev_b32_e32 v160, 5, v160
	v_lshl_add_u64 v[14:15], v[4:5], 0, v[160:161]
	s_nop 1
	global_load_dword v228, v[12:13], off
	global_load_dwordx2 v[196:197], v[14:15], off
	v_mov_b32_e32 v8, 0x4000
	v_mov_b32_e32 v9, 0x2000
	v_cndmask_b32_e64 v160, v8, v9, s[40:41]
	v_lshl_add_u64 v[12:13], v[2:3], 0, v[160:161]
	v_cvt_pk_bf16_f32 v11, v6, v7
	s_nop 1
	global_store_dword v[12:13], v11, off
	s_waitcnt vmcnt(30)
	v_lshlrev_b32_e32 v14, 16, v229
	v_and_b32_e32 v15, 0xffff0000, v229
	s_nop 0
	v_pk_fma_f32 v[6:7], v[6:7], v[198:199], v[14:15]
	v_mov_b32_e32 v8, 0x2e000
	v_mov_b32_e32 v9, 0x20000
	v_cndmask_b32_e64 v160, v8, v9, s[40:41]
	v_lshl_add_u64 v[12:13], v[0:1], 0, v[160:161]
	v_lshrrev_b32_e32 v160, 5, v160
	v_lshl_add_u64 v[14:15], v[4:5], 0, v[160:161]
	s_nop 1
	global_load_dword v229, v[12:13], off
	global_load_dwordx2 v[198:199], v[14:15], off
	v_mov_b32_e32 v8, 0x2000
	v_mov_b32_e32 v9, 0x4000
	v_cndmask_b32_e64 v160, v8, v9, s[40:41]
	v_lshl_add_u64 v[12:13], v[2:3], 0, v[160:161]
	v_cvt_pk_bf16_f32 v11, v6, v7
	s_nop 1
	global_store_dword v[12:13], v11, off
	s_waitcnt vmcnt(31)
	v_lshlrev_b32_e32 v14, 16, v230
	v_and_b32_e32 v15, 0xffff0000, v230
	s_nop 0
	v_pk_fma_f32 v[6:7], v[6:7], v[200:201], v[14:15]
	v_mov_b32_e32 v8, 0x2c000
	v_mov_b32_e32 v9, 0x22000
	v_cndmask_b32_e64 v160, v8, v9, s[40:41]
	v_lshl_add_u64 v[12:13], v[0:1], 0, v[160:161]
	v_lshrrev_b32_e32 v160, 5, v160
	v_lshl_add_u64 v[14:15], v[4:5], 0, v[160:161]
	s_nop 1
	global_load_dword v230, v[12:13], off
	global_load_dwordx2 v[200:201], v[14:15], off
	v_mov_b32_e32 v8, 0x0
	v_mov_b32_e32 v9, 0x6000
	v_cndmask_b32_e64 v160, v8, v9, s[40:41]
	v_lshl_add_u64 v[12:13], v[2:3], 0, v[160:161]
	v_cvt_pk_bf16_f32 v11, v6, v7
	s_nop 1
	global_store_dword v[12:13], v11, off
	s_waitcnt vmcnt(32)
	v_lshlrev_b32_e32 v14, 16, v231
	v_and_b32_e32 v15, 0xffff0000, v231
	s_nop 0
	v_pk_fma_f32 v[6:7], v[6:7], v[202:203], v[14:15]
	v_mov_b32_e32 v8, 0x2a000
	v_mov_b32_e32 v9, 0x24000
	v_cndmask_b32_e64 v160, v8, v9, s[40:41]
	v_lshl_add_u64 v[12:13], v[0:1], 0, v[160:161]
	v_lshrrev_b32_e32 v160, 5, v160
	v_lshl_add_u64 v[14:15], v[4:5], 0, v[160:161]
	s_nop 1
	global_load_dword v231, v[12:13], off
	global_load_dwordx2 v[202:203], v[14:15], off
	v_mov_b32_e32 v8, 0x46000
	v_mov_b32_e32 v9, 0x8000
	v_cndmask_b32_e64 v160, v8, v9, s[40:41]
	v_lshl_add_u64 v[12:13], v[2:3], 0, v[160:161]
	v_cvt_pk_bf16_f32 v11, v6, v7
	s_nop 1
	global_store_dword v[12:13], v11, off
	s_waitcnt vmcnt(33)
	v_lshlrev_b32_e32 v14, 16, v232
	v_and_b32_e32 v15, 0xffff0000, v232
	s_nop 0
	v_pk_fma_f32 v[6:7], v[6:7], v[206:207], v[14:15]
	v_mov_b32_e32 v8, 0x28000
	v_mov_b32_e32 v9, 0x26000
	v_cndmask_b32_e64 v160, v8, v9, s[40:41]
	v_lshl_add_u64 v[12:13], v[0:1], 0, v[160:161]
	v_lshrrev_b32_e32 v160, 5, v160
	v_lshl_add_u64 v[14:15], v[4:5], 0, v[160:161]
	s_nop 1
	global_load_dword v232, v[12:13], off
	global_load_dwordx2 v[206:207], v[14:15], off
	v_mov_b32_e32 v8, 0x44000
	v_mov_b32_e32 v9, 0xa000
	v_cndmask_b32_e64 v160, v8, v9, s[40:41]
	v_lshl_add_u64 v[12:13], v[2:3], 0, v[160:161]
	v_cvt_pk_bf16_f32 v11, v6, v7
	s_nop 1
	global_store_dword v[12:13], v11, off
	s_waitcnt vmcnt(34)
	v_lshlrev_b32_e32 v14, 16, v233
	v_and_b32_e32 v15, 0xffff0000, v233
	s_nop 0
	v_pk_fma_f32 v[6:7], v[6:7], v[208:209], v[14:15]
	v_mov_b32_e32 v8, 0x26000
	v_mov_b32_e32 v9, 0x28000
	v_cndmask_b32_e64 v160, v8, v9, s[40:41]
	v_lshl_add_u64 v[12:13], v[0:1], 0, v[160:161]
	v_lshrrev_b32_e32 v160, 5, v160
	v_lshl_add_u64 v[14:15], v[4:5], 0, v[160:161]
	s_nop 1
	global_load_dword v233, v[12:13], off
	global_load_dwordx2 v[208:209], v[14:15], off
	v_mov_b32_e32 v8, 0x42000
	v_mov_b32_e32 v9, 0xc000
	v_cndmask_b32_e64 v160, v8, v9, s[40:41]
	v_lshl_add_u64 v[12:13], v[2:3], 0, v[160:161]
	v_cvt_pk_bf16_f32 v11, v6, v7
	s_nop 1
	global_store_dword v[12:13], v11, off
	s_waitcnt vmcnt(35)
	v_lshlrev_b32_e32 v14, 16, v234
	v_and_b32_e32 v15, 0xffff0000, v234
	s_nop 0
	v_pk_fma_f32 v[6:7], v[6:7], v[210:211], v[14:15]
	v_mov_b32_e32 v8, 0x24000
	v_mov_b32_e32 v9, 0x2a000
	v_cndmask_b32_e64 v160, v8, v9, s[40:41]
	v_lshl_add_u64 v[12:13], v[0:1], 0, v[160:161]
	v_lshrrev_b32_e32 v160, 5, v160
	v_lshl_add_u64 v[14:15], v[4:5], 0, v[160:161]
	s_nop 1
	global_load_dword v234, v[12:13], off
	global_load_dwordx2 v[210:211], v[14:15], off
	v_mov_b32_e32 v8, 0x40000
	v_mov_b32_e32 v9, 0xe000
	v_cndmask_b32_e64 v160, v8, v9, s[40:41]
	v_lshl_add_u64 v[12:13], v[2:3], 0, v[160:161]
	v_cvt_pk_bf16_f32 v11, v6, v7
	s_nop 1
	global_store_dword v[12:13], v11, off
	s_waitcnt vmcnt(36)
	v_lshlrev_b32_e32 v14, 16, v235
	v_and_b32_e32 v15, 0xffff0000, v235
	s_nop 0
	v_pk_fma_f32 v[6:7], v[6:7], v[212:213], v[14:15]
	v_mov_b32_e32 v8, 0x22000
	v_mov_b32_e32 v9, 0x2c000
	v_cndmask_b32_e64 v160, v8, v9, s[40:41]
	v_lshl_add_u64 v[12:13], v[0:1], 0, v[160:161]
	v_lshrrev_b32_e32 v160, 5, v160
	v_lshl_add_u64 v[14:15], v[4:5], 0, v[160:161]
	s_nop 1
	global_load_dword v235, v[12:13], off
	global_load_dwordx2 v[212:213], v[14:15], off
	v_mov_b32_e32 v8, 0x3e000
	v_mov_b32_e32 v9, 0x10000
	v_cndmask_b32_e64 v160, v8, v9, s[40:41]
	v_lshl_add_u64 v[12:13], v[2:3], 0, v[160:161]
	v_cvt_pk_bf16_f32 v11, v6, v7
	s_nop 1
	global_store_dword v[12:13], v11, off
	s_waitcnt vmcnt(37)
	v_lshlrev_b32_e32 v14, 16, v240
	v_and_b32_e32 v15, 0xffff0000, v240
	s_nop 0
	v_pk_fma_f32 v[6:7], v[6:7], v[214:215], v[14:15]
	v_mov_b32_e32 v8, 0x20000
	v_mov_b32_e32 v9, 0x2e000
	v_cndmask_b32_e64 v160, v8, v9, s[40:41]
	v_lshl_add_u64 v[12:13], v[0:1], 0, v[160:161]
	v_lshrrev_b32_e32 v160, 5, v160
	v_lshl_add_u64 v[14:15], v[4:5], 0, v[160:161]
	s_nop 1
	global_load_dword v240, v[12:13], off
	global_load_dwordx2 v[214:215], v[14:15], off
	v_mov_b32_e32 v8, 0x3c000
	v_mov_b32_e32 v9, 0x12000
	v_cndmask_b32_e64 v160, v8, v9, s[40:41]
	v_lshl_add_u64 v[12:13], v[2:3], 0, v[160:161]
	v_cvt_pk_bf16_f32 v11, v6, v7
	s_nop 1
	global_store_dword v[12:13], v11, off
	s_waitcnt vmcnt(38)
	v_lshlrev_b32_e32 v14, 16, v241
	v_and_b32_e32 v15, 0xffff0000, v241
	s_nop 0
	v_pk_fma_f32 v[6:7], v[6:7], v[216:217], v[14:15]
	v_mov_b32_e32 v8, 0x1e000
	v_mov_b32_e32 v9, 0x30000
	v_cndmask_b32_e64 v160, v8, v9, s[40:41]
	v_lshl_add_u64 v[12:13], v[0:1], 0, v[160:161]
	v_lshrrev_b32_e32 v160, 5, v160
	v_lshl_add_u64 v[14:15], v[4:5], 0, v[160:161]
	s_nop 1
	global_load_dword v241, v[12:13], off
	global_load_dwordx2 v[216:217], v[14:15], off
	v_mov_b32_e32 v8, 0x3a000
	v_mov_b32_e32 v9, 0x14000
	v_cndmask_b32_e64 v160, v8, v9, s[40:41]
	v_lshl_add_u64 v[12:13], v[2:3], 0, v[160:161]
	v_cvt_pk_bf16_f32 v11, v6, v7
	s_nop 1
	global_store_dword v[12:13], v11, off
	s_waitcnt vmcnt(39)
	v_lshlrev_b32_e32 v14, 16, v242
	v_and_b32_e32 v15, 0xffff0000, v242
	s_nop 0
	v_pk_fma_f32 v[6:7], v[6:7], v[218:219], v[14:15]
	v_mov_b32_e32 v8, 0x1c000
	v_mov_b32_e32 v9, 0x32000
	v_cndmask_b32_e64 v160, v8, v9, s[40:41]
	v_lshl_add_u64 v[12:13], v[0:1], 0, v[160:161]
	v_lshrrev_b32_e32 v160, 5, v160
	v_lshl_add_u64 v[14:15], v[4:5], 0, v[160:161]
	s_nop 1
	global_load_dword v242, v[12:13], off
	global_load_dwordx2 v[218:219], v[14:15], off
	v_mov_b32_e32 v8, 0x38000
	v_mov_b32_e32 v9, 0x16000
	v_cndmask_b32_e64 v160, v8, v9, s[40:41]
	v_lshl_add_u64 v[12:13], v[2:3], 0, v[160:161]
	v_cvt_pk_bf16_f32 v11, v6, v7
	s_nop 1
	global_store_dword v[12:13], v11, off
	s_waitcnt vmcnt(40)
	v_lshlrev_b32_e32 v14, 16, v243
	v_and_b32_e32 v15, 0xffff0000, v243
	s_nop 0
	v_pk_fma_f32 v[6:7], v[6:7], v[220:221], v[14:15]
	v_mov_b32_e32 v8, 0x1a000
	v_mov_b32_e32 v9, 0x34000
	v_cndmask_b32_e64 v160, v8, v9, s[40:41]
	v_lshl_add_u64 v[12:13], v[0:1], 0, v[160:161]
	v_lshrrev_b32_e32 v160, 5, v160
	v_lshl_add_u64 v[14:15], v[4:5], 0, v[160:161]
	s_nop 1
	global_load_dword v243, v[12:13], off
	global_load_dwordx2 v[220:221], v[14:15], off
	v_mov_b32_e32 v8, 0x36000
	v_mov_b32_e32 v9, 0x18000
	v_cndmask_b32_e64 v160, v8, v9, s[40:41]
	v_lshl_add_u64 v[12:13], v[2:3], 0, v[160:161]
	v_cvt_pk_bf16_f32 v11, v6, v7
	s_nop 1
	global_store_dword v[12:13], v11, off
	s_waitcnt vmcnt(41)
	v_lshlrev_b32_e32 v14, 16, v248
	v_and_b32_e32 v15, 0xffff0000, v248
	s_nop 0
	v_pk_fma_f32 v[6:7], v[6:7], v[222:223], v[14:15]
	v_mov_b32_e32 v8, 0x18000
	v_mov_b32_e32 v9, 0x36000
	v_cndmask_b32_e64 v160, v8, v9, s[40:41]
	v_lshl_add_u64 v[12:13], v[0:1], 0, v[160:161]
	v_lshrrev_b32_e32 v160, 5, v160
	v_lshl_add_u64 v[14:15], v[4:5], 0, v[160:161]
	s_nop 1
	global_load_dword v248, v[12:13], off
	global_load_dwordx2 v[222:223], v[14:15], off
	v_mov_b32_e32 v8, 0x34000
	v_mov_b32_e32 v9, 0x1a000
	v_cndmask_b32_e64 v160, v8, v9, s[40:41]
	v_lshl_add_u64 v[12:13], v[2:3], 0, v[160:161]
	v_cvt_pk_bf16_f32 v11, v6, v7
	s_nop 1
	global_store_dword v[12:13], v11, off
	s_waitcnt vmcnt(42)
	v_lshlrev_b32_e32 v14, 16, v249
	v_and_b32_e32 v15, 0xffff0000, v249
	s_nop 0
	v_pk_fma_f32 v[6:7], v[6:7], v[224:225], v[14:15]
	v_mov_b32_e32 v8, 0x16000
	v_mov_b32_e32 v9, 0x38000
	v_cndmask_b32_e64 v160, v8, v9, s[40:41]
	v_lshl_add_u64 v[12:13], v[0:1], 0, v[160:161]
	v_lshrrev_b32_e32 v160, 5, v160
	v_lshl_add_u64 v[14:15], v[4:5], 0, v[160:161]
	s_nop 1
	global_load_dword v249, v[12:13], off
	global_load_dwordx2 v[224:225], v[14:15], off
	v_mov_b32_e32 v8, 0x32000
	v_mov_b32_e32 v9, 0x1c000
	v_cndmask_b32_e64 v160, v8, v9, s[40:41]
	v_lshl_add_u64 v[12:13], v[2:3], 0, v[160:161]
	v_cvt_pk_bf16_f32 v11, v6, v7
	s_nop 1
	global_store_dword v[12:13], v11, off
	s_waitcnt vmcnt(43)
	v_lshlrev_b32_e32 v14, 16, v250
	v_and_b32_e32 v15, 0xffff0000, v250
	s_nop 0
	v_pk_fma_f32 v[6:7], v[6:7], v[226:227], v[14:15]
	v_mov_b32_e32 v8, 0x14000
	v_mov_b32_e32 v9, 0x3a000
	v_cndmask_b32_e64 v160, v8, v9, s[40:41]
	v_lshl_add_u64 v[12:13], v[0:1], 0, v[160:161]
	v_lshrrev_b32_e32 v160, 5, v160
	v_lshl_add_u64 v[14:15], v[4:5], 0, v[160:161]
	s_nop 1
	global_load_dword v250, v[12:13], off
	global_load_dwordx2 v[226:227], v[14:15], off
	v_mov_b32_e32 v8, 0x30000
	v_mov_b32_e32 v9, 0x1e000
	v_cndmask_b32_e64 v160, v8, v9, s[40:41]
	v_lshl_add_u64 v[12:13], v[2:3], 0, v[160:161]
	v_cvt_pk_bf16_f32 v11, v6, v7
	s_nop 1
	global_store_dword v[12:13], v11, off
	s_waitcnt vmcnt(43)
	v_lshlrev_b32_e32 v14, 16, v228
	v_and_b32_e32 v15, 0xffff0000, v228
	s_nop 0
	v_pk_fma_f32 v[6:7], v[6:7], v[196:197], v[14:15]
	v_mov_b32_e32 v8, 0x12000
	v_mov_b32_e32 v9, 0x3c000
	v_cndmask_b32_e64 v160, v8, v9, s[40:41]
	v_lshl_add_u64 v[12:13], v[0:1], 0, v[160:161]
	v_lshrrev_b32_e32 v160, 5, v160
	v_lshl_add_u64 v[14:15], v[4:5], 0, v[160:161]
	s_nop 1
	global_load_dword v228, v[12:13], off
	global_load_dwordx2 v[196:197], v[14:15], off
	v_mov_b32_e32 v8, 0x2e000
	v_mov_b32_e32 v9, 0x20000
	v_cndmask_b32_e64 v160, v8, v9, s[40:41]
	v_lshl_add_u64 v[12:13], v[2:3], 0, v[160:161]
	v_cvt_pk_bf16_f32 v11, v6, v7
	s_nop 1
	global_store_dword v[12:13], v11, off
	s_waitcnt vmcnt(43)
	v_lshlrev_b32_e32 v14, 16, v229
	v_and_b32_e32 v15, 0xffff0000, v229
	s_nop 0
	v_pk_fma_f32 v[6:7], v[6:7], v[198:199], v[14:15]
	v_mov_b32_e32 v8, 0x10000
	v_mov_b32_e32 v9, 0x3e000
	v_cndmask_b32_e64 v160, v8, v9, s[40:41]
	v_lshl_add_u64 v[12:13], v[0:1], 0, v[160:161]
	v_lshrrev_b32_e32 v160, 5, v160
	v_lshl_add_u64 v[14:15], v[4:5], 0, v[160:161]
	s_nop 1
	global_load_dword v229, v[12:13], off
	global_load_dwordx2 v[198:199], v[14:15], off
	v_mov_b32_e32 v8, 0x2c000
	v_mov_b32_e32 v9, 0x22000
	v_cndmask_b32_e64 v160, v8, v9, s[40:41]
	v_lshl_add_u64 v[12:13], v[2:3], 0, v[160:161]
	v_cvt_pk_bf16_f32 v11, v6, v7
	s_nop 1
	global_store_dword v[12:13], v11, off
	s_waitcnt vmcnt(43)
	v_lshlrev_b32_e32 v14, 16, v230
	v_and_b32_e32 v15, 0xffff0000, v230
	s_nop 0
	v_pk_fma_f32 v[6:7], v[6:7], v[200:201], v[14:15]
	v_mov_b32_e32 v8, 0xe000
	v_mov_b32_e32 v9, 0x40000
	v_cndmask_b32_e64 v160, v8, v9, s[40:41]
	v_lshl_add_u64 v[12:13], v[0:1], 0, v[160:161]
	v_lshrrev_b32_e32 v160, 5, v160
	v_lshl_add_u64 v[14:15], v[4:5], 0, v[160:161]
	s_nop 1
	global_load_dword v230, v[12:13], off
	global_load_dwordx2 v[200:201], v[14:15], off
	v_mov_b32_e32 v8, 0x2a000
	v_mov_b32_e32 v9, 0x24000
	v_cndmask_b32_e64 v160, v8, v9, s[40:41]
	v_lshl_add_u64 v[12:13], v[2:3], 0, v[160:161]
	v_cvt_pk_bf16_f32 v11, v6, v7
	s_nop 1
	global_store_dword v[12:13], v11, off
	s_waitcnt vmcnt(43)
	v_lshlrev_b32_e32 v14, 16, v231
	v_and_b32_e32 v15, 0xffff0000, v231
	s_nop 0
	v_pk_fma_f32 v[6:7], v[6:7], v[202:203], v[14:15]
	v_mov_b32_e32 v8, 0xc000
	v_mov_b32_e32 v9, 0x42000
	v_cndmask_b32_e64 v160, v8, v9, s[40:41]
	v_lshl_add_u64 v[12:13], v[0:1], 0, v[160:161]
	v_lshrrev_b32_e32 v160, 5, v160
	v_lshl_add_u64 v[14:15], v[4:5], 0, v[160:161]
	s_nop 1
	global_load_dword v231, v[12:13], off
	global_load_dwordx2 v[202:203], v[14:15], off
	v_mov_b32_e32 v8, 0x28000
	v_mov_b32_e32 v9, 0x26000
	v_cndmask_b32_e64 v160, v8, v9, s[40:41]
	v_lshl_add_u64 v[12:13], v[2:3], 0, v[160:161]
	v_cvt_pk_bf16_f32 v11, v6, v7
	s_nop 1
	global_store_dword v[12:13], v11, off
	s_waitcnt vmcnt(43)
	v_lshlrev_b32_e32 v14, 16, v232
	v_and_b32_e32 v15, 0xffff0000, v232
	s_nop 0
	v_pk_fma_f32 v[6:7], v[6:7], v[206:207], v[14:15]
	v_mov_b32_e32 v8, 0xa000
	v_mov_b32_e32 v9, 0x44000
	v_cndmask_b32_e64 v160, v8, v9, s[40:41]
	v_lshl_add_u64 v[12:13], v[0:1], 0, v[160:161]
	v_lshrrev_b32_e32 v160, 5, v160
	v_lshl_add_u64 v[14:15], v[4:5], 0, v[160:161]
	s_nop 1
	global_load_dword v232, v[12:13], off
	global_load_dwordx2 v[206:207], v[14:15], off
	v_mov_b32_e32 v8, 0x26000
	v_mov_b32_e32 v9, 0x28000
	v_cndmask_b32_e64 v160, v8, v9, s[40:41]
	v_lshl_add_u64 v[12:13], v[2:3], 0, v[160:161]
	v_cvt_pk_bf16_f32 v11, v6, v7
	s_nop 1
	global_store_dword v[12:13], v11, off
	s_waitcnt vmcnt(43)
	v_lshlrev_b32_e32 v14, 16, v233
	v_and_b32_e32 v15, 0xffff0000, v233
	s_nop 0
	v_pk_fma_f32 v[6:7], v[6:7], v[208:209], v[14:15]
	v_mov_b32_e32 v8, 0x8000
	v_mov_b32_e32 v9, 0x46000
	v_cndmask_b32_e64 v160, v8, v9, s[40:41]
	v_lshl_add_u64 v[12:13], v[0:1], 0, v[160:161]
	v_lshrrev_b32_e32 v160, 5, v160
	v_lshl_add_u64 v[14:15], v[4:5], 0, v[160:161]
	s_nop 1
	global_load_dword v233, v[12:13], off
	global_load_dwordx2 v[208:209], v[14:15], off
	v_mov_b32_e32 v8, 0x24000
	v_mov_b32_e32 v9, 0x2a000
	v_cndmask_b32_e64 v160, v8, v9, s[40:41]
	v_lshl_add_u64 v[12:13], v[2:3], 0, v[160:161]
	v_cvt_pk_bf16_f32 v11, v6, v7
	s_nop 1
	global_store_dword v[12:13], v11, off
	s_waitcnt vmcnt(43)
	v_lshlrev_b32_e32 v14, 16, v234
	v_and_b32_e32 v15, 0xffff0000, v234
	s_nop 0
	v_pk_fma_f32 v[6:7], v[6:7], v[210:211], v[14:15]
	v_mov_b32_e32 v8, 0x22000
	v_mov_b32_e32 v9, 0x2c000
	v_cndmask_b32_e64 v160, v8, v9, s[40:41]
	v_lshl_add_u64 v[12:13], v[2:3], 0, v[160:161]
	v_cvt_pk_bf16_f32 v11, v6, v7
	s_nop 1
	global_store_dword v[12:13], v11, off
	s_waitcnt vmcnt(41)
	v_lshlrev_b32_e32 v14, 16, v235
	v_and_b32_e32 v15, 0xffff0000, v235
	s_nop 0
	v_pk_fma_f32 v[6:7], v[6:7], v[212:213], v[14:15]
	v_mov_b32_e32 v8, 0x20000
	v_mov_b32_e32 v9, 0x2e000
	v_cndmask_b32_e64 v160, v8, v9, s[40:41]
	v_lshl_add_u64 v[12:13], v[2:3], 0, v[160:161]
	v_cvt_pk_bf16_f32 v11, v6, v7
	s_nop 1
	global_store_dword v[12:13], v11, off
	s_waitcnt vmcnt(39)
	v_lshlrev_b32_e32 v14, 16, v240
	v_and_b32_e32 v15, 0xffff0000, v240
	s_nop 0
	v_pk_fma_f32 v[6:7], v[6:7], v[214:215], v[14:15]
	v_mov_b32_e32 v8, 0x1e000
	v_mov_b32_e32 v9, 0x30000
	v_cndmask_b32_e64 v160, v8, v9, s[40:41]
	v_lshl_add_u64 v[12:13], v[2:3], 0, v[160:161]
	v_cvt_pk_bf16_f32 v11, v6, v7
	s_nop 1
	global_store_dword v[12:13], v11, off
	s_waitcnt vmcnt(37)
	v_lshlrev_b32_e32 v14, 16, v241
	v_and_b32_e32 v15, 0xffff0000, v241
	s_nop 0
	v_pk_fma_f32 v[6:7], v[6:7], v[216:217], v[14:15]
	v_mov_b32_e32 v8, 0x1c000
	v_mov_b32_e32 v9, 0x32000
	v_cndmask_b32_e64 v160, v8, v9, s[40:41]
	v_lshl_add_u64 v[12:13], v[2:3], 0, v[160:161]
	v_cvt_pk_bf16_f32 v11, v6, v7
	s_nop 1
	global_store_dword v[12:13], v11, off
	s_waitcnt vmcnt(35)
	v_lshlrev_b32_e32 v14, 16, v242
	v_and_b32_e32 v15, 0xffff0000, v242
	s_nop 0
	v_pk_fma_f32 v[6:7], v[6:7], v[218:219], v[14:15]
	v_mov_b32_e32 v8, 0x1a000
	v_mov_b32_e32 v9, 0x34000
	v_cndmask_b32_e64 v160, v8, v9, s[40:41]
	v_lshl_add_u64 v[12:13], v[2:3], 0, v[160:161]
	v_cvt_pk_bf16_f32 v11, v6, v7
	s_nop 1
	global_store_dword v[12:13], v11, off
	s_waitcnt vmcnt(33)
	v_lshlrev_b32_e32 v14, 16, v243
	v_and_b32_e32 v15, 0xffff0000, v243
	s_nop 0
	v_pk_fma_f32 v[6:7], v[6:7], v[220:221], v[14:15]
	v_mov_b32_e32 v8, 0x18000
	v_mov_b32_e32 v9, 0x36000
	v_cndmask_b32_e64 v160, v8, v9, s[40:41]
	v_lshl_add_u64 v[12:13], v[2:3], 0, v[160:161]
	v_cvt_pk_bf16_f32 v11, v6, v7
	s_nop 1
	global_store_dword v[12:13], v11, off
	s_waitcnt vmcnt(31)
	v_lshlrev_b32_e32 v14, 16, v248
	v_and_b32_e32 v15, 0xffff0000, v248
	s_nop 0
	v_pk_fma_f32 v[6:7], v[6:7], v[222:223], v[14:15]
	v_mov_b32_e32 v8, 0x16000
	v_mov_b32_e32 v9, 0x38000
	v_cndmask_b32_e64 v160, v8, v9, s[40:41]
	v_lshl_add_u64 v[12:13], v[2:3], 0, v[160:161]
	v_cvt_pk_bf16_f32 v11, v6, v7
	s_nop 1
	global_store_dword v[12:13], v11, off
	s_waitcnt vmcnt(29)
	v_lshlrev_b32_e32 v14, 16, v249
	v_and_b32_e32 v15, 0xffff0000, v249
	s_nop 0
	v_pk_fma_f32 v[6:7], v[6:7], v[224:225], v[14:15]
	v_mov_b32_e32 v8, 0x14000
	v_mov_b32_e32 v9, 0x3a000
	v_cndmask_b32_e64 v160, v8, v9, s[40:41]
	v_lshl_add_u64 v[12:13], v[2:3], 0, v[160:161]
	v_cvt_pk_bf16_f32 v11, v6, v7
	s_nop 1
	global_store_dword v[12:13], v11, off
	s_waitcnt vmcnt(27)
	v_lshlrev_b32_e32 v14, 16, v250
	v_and_b32_e32 v15, 0xffff0000, v250
	s_nop 0
	v_pk_fma_f32 v[6:7], v[6:7], v[226:227], v[14:15]
	v_mov_b32_e32 v8, 0x12000
	v_mov_b32_e32 v9, 0x3c000
	v_cndmask_b32_e64 v160, v8, v9, s[40:41]
	v_lshl_add_u64 v[12:13], v[2:3], 0, v[160:161]
	v_cvt_pk_bf16_f32 v11, v6, v7
	s_nop 1
	global_store_dword v[12:13], v11, off
	s_waitcnt vmcnt(25)
	v_lshlrev_b32_e32 v14, 16, v228
	v_and_b32_e32 v15, 0xffff0000, v228
	s_nop 0
	v_pk_fma_f32 v[6:7], v[6:7], v[196:197], v[14:15]
	v_mov_b32_e32 v8, 0x10000
	v_mov_b32_e32 v9, 0x3e000
	v_cndmask_b32_e64 v160, v8, v9, s[40:41]
	v_lshl_add_u64 v[12:13], v[2:3], 0, v[160:161]
	v_cvt_pk_bf16_f32 v11, v6, v7
	s_nop 1
	global_store_dword v[12:13], v11, off
	s_waitcnt vmcnt(23)
	v_lshlrev_b32_e32 v14, 16, v229
	v_and_b32_e32 v15, 0xffff0000, v229
	s_nop 0
	v_pk_fma_f32 v[6:7], v[6:7], v[198:199], v[14:15]
	v_mov_b32_e32 v8, 0xe000
	v_mov_b32_e32 v9, 0x40000
	v_cndmask_b32_e64 v160, v8, v9, s[40:41]
	v_lshl_add_u64 v[12:13], v[2:3], 0, v[160:161]
	v_cvt_pk_bf16_f32 v11, v6, v7
	s_nop 1
	global_store_dword v[12:13], v11, off
	s_waitcnt vmcnt(21)
	v_lshlrev_b32_e32 v14, 16, v230
	v_and_b32_e32 v15, 0xffff0000, v230
	s_nop 0
	v_pk_fma_f32 v[6:7], v[6:7], v[200:201], v[14:15]
	v_mov_b32_e32 v8, 0xc000
	v_mov_b32_e32 v9, 0x42000
	v_cndmask_b32_e64 v160, v8, v9, s[40:41]
	v_lshl_add_u64 v[12:13], v[2:3], 0, v[160:161]
	v_cvt_pk_bf16_f32 v11, v6, v7
	s_nop 1
	global_store_dword v[12:13], v11, off
	s_waitcnt vmcnt(19)
	v_lshlrev_b32_e32 v14, 16, v231
	v_and_b32_e32 v15, 0xffff0000, v231
	s_nop 0
	v_pk_fma_f32 v[6:7], v[6:7], v[202:203], v[14:15]
	v_mov_b32_e32 v8, 0xa000
	v_mov_b32_e32 v9, 0x44000
	v_cndmask_b32_e64 v160, v8, v9, s[40:41]
	v_lshl_add_u64 v[12:13], v[2:3], 0, v[160:161]
	v_cvt_pk_bf16_f32 v11, v6, v7
	s_nop 1
	global_store_dword v[12:13], v11, off
	s_waitcnt vmcnt(17)
	v_lshlrev_b32_e32 v14, 16, v232
	v_and_b32_e32 v15, 0xffff0000, v232
	s_nop 0
	v_pk_fma_f32 v[6:7], v[6:7], v[206:207], v[14:15]
	v_mov_b32_e32 v8, 0x8000
	v_mov_b32_e32 v9, 0x46000
	v_cndmask_b32_e64 v160, v8, v9, s[40:41]
	v_lshl_add_u64 v[12:13], v[2:3], 0, v[160:161]
	v_cvt_pk_bf16_f32 v11, v6, v7
	s_nop 1
	global_store_dword v[12:13], v11, off
	s_waitcnt vmcnt(15)
	v_lshlrev_b32_e32 v14, 16, v233
	v_and_b32_e32 v15, 0xffff0000, v233
	s_nop 0
	v_pk_fma_f32 v[6:7], v[6:7], v[208:209], v[14:15]
	s_branch .LBB0_382
